# P2 mLSTM local-unit loop software-pipelined by hand: next unit V tile + gate pre-activations requested before the conv barrier, conv input rows after the conv, counted vmcnt waits
# speedup vs baseline: 1.0322x; 1.0077x over previous
.LBB0_282:
	s_cmp_lt_i32 s80, 3
	s_cselect_b64 s[30:31], -1, 0
	s_add_u32 s28, s88, 0x3d00000
	s_addc_u32 s29, s89, 0
	s_add_u32 s78, s88, 0x1f200000
	s_addc_u32 s79, s89, 0
	s_add_u32 s26, s88, 0x16000000
	s_addc_u32 s27, s89, 0
	s_and_b64 s[0:1], s[30:31], s[0:1]
	s_andn2_b64 vcc, exec, s[0:1]
	s_cbranch_vccnz .LBB0_324
	v_readlane_b32 s0, v250, 0
	v_mov_b32_e32 v68, v204
	s_cmpk_gt_i32 s0, 0x7ff
	s_nop 0
	v_readfirstlane_b32 s25, v68
	v_bfe_u32 v87, v68, 4, 2
	v_bfe_u32 v88, v68, 2, 2
	v_and_b32_e32 v90, 15, v68
	v_lshlrev_b32_e32 v89, 3, v68
	v_lshrrev_b32_e32 v86, 2, v68
	s_cbranch_scc1 .LBB0_309
	s_mov_b32 s0, 0x2aaaaaab
	v_mul_hi_i32 v0, v68, s0
	v_lshrrev_b32_e32 v1, 31, v0
	v_ashrrev_i32_e32 v0, 2, v0
	v_add_u32_e32 v70, v0, v1
	v_add_u32_e32 v1, 0x200, v68
	v_mul_hi_i32 v2, v1, s0
	v_lshrrev_b32_e32 v3, 31, v2
	v_ashrrev_i32_e32 v2, 2, v2
	v_add_u32_e32 v74, v2, v3
	v_mul_lo_u32 v2, v74, 24
	v_sub_u32_e32 v1, v1, v2
	v_add_u32_e32 v2, 0x400, v68
	v_mul_lo_u32 v0, v70, 24
	v_mul_hi_i32 v3, v2, s0
	v_sub_u32_e32 v0, v68, v0
	v_lshrrev_b32_e32 v4, 31, v3
	v_ashrrev_i32_e32 v3, 2, v3
	s_movk_i32 s16, 0x190
	v_lshlrev_b32_e32 v72, 3, v0
	v_add_u32_e32 v78, v3, v4
	v_lshlrev_b32_e32 v5, 4, v0
	v_mul_lo_u32 v0, v74, s16
	v_ashrrev_i32_e32 v69, 31, v68
	v_add_u32_e32 v6, 0, v0
	v_mul_lo_u32 v0, v78, s16
	s_movk_i32 s18, 0xffe8
	v_lshlrev_b32_e32 v76, 3, v1
	v_lshlrev_b32_e32 v7, 4, v1
	v_add_u32_e32 v8, 0, v0
	v_mad_u64_u32 v[0:1], s[18:19], v70, s18, v[68:69]
	v_mov_b32_e32 v93, 0x300
	s_movk_i32 s18, 0x640
	s_add_u32 s50, s88, 0x3f00000
	v_mul_lo_u32 v3, v78, 24
	v_lshl_add_u32 v94, v0, 3, v93
	v_lshl_add_u32 v0, v0, 4, 0
	v_mul_lo_u32 v1, v70, s18
	s_addc_u32 s51, s89, 0
	v_sub_u32_e32 v2, v2, v3
	v_mul_lo_u32 v4, v70, s16
	v_lshl_or_b32 v10, v87, 3, v88
	v_add_u32_e32 v104, v0, v1
	v_mbcnt_lo_u32_b32 v0, -1, 0
	s_add_u32 s52, s88, 0x3f02000
	v_lshlrev_b32_e32 v80, 3, v2
	v_and_b32_e32 v3, 63, v68
	v_add_u32_e32 v4, 0, v4
	v_lshlrev_b32_e32 v2, 4, v2
	s_movk_i32 s16, 0x180
	v_and_b32_e32 v9, 24, v89
	v_mul_u32_u24_e32 v10, 0x190, v10
	s_movk_i32 s18, 0xc0
	v_mbcnt_hi_u32_b32 v108, -1, v0
	v_bfrev_b32_e32 v0, 0.5
	v_readlane_b32 s34, v250, 0
	s_addc_u32 s53, s89, 0
	v_ashrrev_i32_e32 v71, 31, v70
	v_ashrrev_i32_e32 v73, 31, v72
	v_ashrrev_i32_e32 v75, 31, v74
	v_ashrrev_i32_e32 v77, 31, v76
	v_ashrrev_i32_e32 v79, 31, v78
	v_ashrrev_i32_e32 v81, 31, v80
	v_cmp_gt_i32_e64 s[0:1], 64, v68
	s_mov_b32 s35, 0
	v_cmp_eq_u32_e64 s[20:21], 0, v3
	v_cmp_gt_u32_e64 s[4:5], 2, v3
	v_cmp_gt_u32_e64 s[6:7], 4, v3
	v_cmp_gt_u32_e64 s[8:9], 8, v3
	v_cmp_gt_u32_e64 s[10:11], 16, v3
	v_cmp_gt_u32_e64 s[12:13], 32, v3
	v_lshl_add_u32 v91, v68, 2, 0
	v_cmp_eq_u32_e64 s[14:15], 0, v68
	v_cmp_gt_i32_e64 s[16:17], s16, v68
	v_lshlrev_b32_e32 v92, 2, v70
	v_lshl_add_u32 v95, v70, 4, 0
	v_add3_u32 v96, 0, v9, v10
	v_bfe_u32 v97, v3, 4, 1
	v_and_b32_e32 v98, 8, v86
	v_cmp_gt_i32_e64 s[18:19], s18, v68
	v_lshl_add_u32 v99, v68, 1, 0
	v_lshl_add_u64 v[82:83], v[68:69], 2, s[28:29]
	s_movk_i32 s54, 0x1c00
	v_mov_b32_e32 v100, 0x3ecc95a3
	s_mov_b32 s55, 0x3f317218
	s_mov_b32 s62, 0x7f800000
	s_mov_b32 s63, 0x33800000
	v_mov_b32_e32 v85, 0
	v_add_u32_e32 v101, v4, v5
	v_add_u32_e32 v102, v6, v7
	v_add_u32_e32 v103, v8, v2
	s_mov_b64 s[36:37], 0x1800
	s_mov_b64 s[38:39], 0x3000
	s_mov_b64 s[40:41], 0x4800
	v_mov_b32_e32 v105, 0x7f800000
	v_mov_b32_e32 v106, 0x7fc00000
	v_mov_b32_e32 v107, 0xff800000
	v_lshl_or_b32 v109, v108, 2, v0
	s_mov_b32 s42, s34
	v_readfirstlane_b32 s64, v68
	s_ashr_i32 s44, s42, 8
	s_lshl_b32 s45, s42, 6
	s_lshl_b32 s44, s44, 12
	s_and_b32 s65, s45, 0xfc0
	s_or_b32 s48, s44, s65
	s_bfe_u32 s43, s42, 0x20006
	s_mul_i32 s72, s43, 0xc0
	s_lshl_b32 s45, s72, 1
	s_lshl_b32 s43, s43, 2
	v_add_u32_e32 v196, s48, v70
	v_add_u32_e32 v197, s48, v74
	v_add_u32_e32 v198, s48, v78
	v_mul_lo_u32 v196, v196, s54
	v_mul_lo_u32 v197, v197, s54
	v_mul_lo_u32 v198, v198, s54
	v_lshl_add_u32 v196, v72, 1, v196
	v_lshl_add_u32 v197, v76, 1, v197
	v_lshl_add_u32 v198, v80, 1, v198
	v_add_u32_e32 v196, s45, v196
	v_add_u32_e32 v197, s45, v197
	v_add_u32_e32 v198, s45, v198
	global_load_dwordx4 v[168:171], v196, s[60:61] offset:3072
	global_load_dwordx4 v[172:175], v197, s[60:61] offset:3072
	global_load_dwordx4 v[176:179], v198, s[60:61] offset:3072
	s_and_saveexec_b64 s[46:47], s[0:1]
	s_cbranch_execz .Lp2_pf_g_a
	v_add_u32_e32 v199, s48, v68
	v_lshlrev_b32_e32 v199, 5, v199
	v_add_u32_e32 v199, s43, v199
	v_mov_b32_e32 v200, s43
	global_load_dword v180, v199, s[78:79] offset:16
	global_load_dword v182, v200, s[66:67] offset:16
	global_load_dword v181, v199, s[78:79]
	global_load_dword v183, v200, s[66:67]
.Lp2_pf_g_a:
	s_or_b64 exec, exec, s[46:47]
	s_and_saveexec_b64 s[46:47], s[16:17]
	s_cbranch_execz .Lp2_pf_r_a
	v_add_u32_e32 v199, s72, v94
	v_add_u32_e32 v200, s65, v92
	v_cmp_ne_u32_e32 vcc, 0, v200
	v_add_u32_e32 v201, s44, v200
	v_mul_lo_u32 v201, v201, s54
	v_lshl_add_u32 v201, v199, 1, v201
	v_lshlrev_b32_e32 v189, 2, v199
	v_add_u32_e32 v193, 0x1800, v189
	v_add_u32_e32 v194, 0x3000, v189
	v_add_u32_e32 v195, 0x4800, v189
	v_add_u32_e32 v196, 0xffffac00, v201
	v_add_u32_e32 v197, 0xffffc800, v201
	v_add_u32_e32 v198, 0xffffe400, v201
	v_add_u32_e32 v202, 0x1c00, v201
	v_add_u32_e32 v203, 0x3800, v201
	v_add_u32_e32 v200, 0x5400, v201
	v_mov_b32_e32 v206, 0
	v_mov_b32_e32 v207, 0
	v_mov_b32_e32 v208, 0
	v_mov_b32_e32 v209, 0
	v_mov_b32_e32 v210, 0
	v_mov_b32_e32 v211, 0
	v_mov_b32_e32 v212, 0
	v_mov_b32_e32 v213, 0
	v_mov_b32_e32 v214, 0
	v_mov_b32_e32 v215, 0
	v_mov_b32_e32 v216, 0
	v_mov_b32_e32 v217, 0
	s_and_b64 exec, exec, vcc
	global_load_dwordx4 v[206:209], v196, s[60:61]
	global_load_dwordx4 v[210:213], v197, s[60:61]
	global_load_dwordx4 v[214:217], v198, s[60:61]
	s_mov_b64 exec, s[16:17]
	global_load_dwordx4 v[218:221], v201, s[60:61]
	global_load_dwordx4 v[230:233], v202, s[60:61]
	global_load_dwordx4 v[226:229], v203, s[60:61]
	global_load_dwordx4 v[222:225], v200, s[60:61]
.Lp2_pf_r_a:
	s_or_b64 exec, exec, s[46:47]
	s_waitcnt vmcnt(0)
	s_branch .LBB0_286

.LBB0_286:
	s_cmpk_lt_u32 s64, 0x180
	s_cbranch_scc1 .Lp2_top_c
	s_waitcnt vmcnt(9)
	s_branch .Lp2_top_done
.Lp2_top_c:
	s_cmpk_lt_u32 s64, 0xc0
	s_cbranch_scc1 .Lp2_top_b
	s_waitcnt vmcnt(16)
	s_branch .Lp2_top_done
.Lp2_top_b:
	s_cmp_eq_u32 s64, 0
	s_cbranch_scc1 .Lp2_top_a
	s_waitcnt vmcnt(17)
	s_branch .Lp2_top_done
.Lp2_top_a:
	s_waitcnt vmcnt(19)
.Lp2_top_done:
	s_waitcnt lgkmcnt(0)
	s_barrier
	s_and_saveexec_b64 s[46:47], s[16:17]
	s_cbranch_execz .Lp2_w_skip
	global_load_dwordx4 v[48:51], v189, s[68:69]
	global_load_dwordx4 v[56:59], v189, s[70:71]
	global_load_dwordx4 v[52:55], v193, s[68:69]
	global_load_dwordx4 v[60:63], v194, s[68:69]
	global_load_dwordx4 v[64:67], v195, s[68:69]
	global_load_dwordx4 v[28:31], v189, s[68:69] offset:16
	global_load_dwordx4 v[32:35], v189, s[70:71] offset:16
	global_load_dwordx4 v[36:39], v193, s[68:69] offset:16
	global_load_dwordx4 v[40:43], v194, s[68:69] offset:16
	global_load_dwordx4 v[44:47], v195, s[68:69] offset:16
.Lp2_w_skip:
	s_or_b64 exec, exec, s[46:47]
	s_and_saveexec_b64 s[46:47], s[0:1]
	s_cbranch_execz .LBB0_289
	s_mov_b32 s43, 0xbfb8aa3b
	v_and_b32_e32 v14, 64, v108
	v_add_u32_e32 v15, -1, v108
	s_mov_b32 s34, 0x3f2aaaab
	v_cmp_lt_i32_e32 vcc, v15, v14
	v_add_f32_e32 v16, v180, v182
	v_mul_f32_e64 v17, |v16|, s43
	v_exp_f32_e32 v18, v17
	v_min_f32_e32 v19, 0, v16
	v_cndmask_b32_e32 v15, v15, v108, vcc
	v_lshlrev_b32_e32 v15, 2, v15
	v_add_f32_e32 v20, 1.0, v18
	v_add_f32_e32 v21, -1.0, v20
	v_frexp_mant_f32_e32 v22, v20
	v_cvt_f64_f32_e32 v[16:17], v20
	v_sub_f32_e32 v23, v21, v20
	v_frexp_exp_i32_f64_e32 v16, v[16:17]
	v_cmp_gt_f32_e32 vcc, s34, v22
	v_sub_f32_e32 v21, v18, v21
	v_add_f32_e32 v17, 1.0, v23
	v_subbrev_co_u32_e32 v16, vcc, 0, v16, vcc
	v_add_f32_e32 v17, v21, v17
	v_sub_u32_e32 v21, 0, v16
	v_cvt_f32_i32_e32 v16, v16
	v_ldexp_f32 v20, v20, v21
	v_ldexp_f32 v17, v17, v21
	v_add_f32_e32 v21, -1.0, v20
	v_add_f32_e32 v22, 1.0, v20
	v_add_f32_e32 v23, 1.0, v21
	v_add_f32_e32 v24, -1.0, v22
	v_sub_f32_e32 v23, v20, v23
	v_sub_f32_e32 v20, v20, v24
	v_mul_f32_e32 v24, 0x3f317218, v16
	v_add_f32_e32 v23, v17, v23
	v_add_f32_e32 v17, v17, v20
	v_fma_f32 v20, v16, s55, -v24
	v_add_f32_e32 v25, v21, v23
	v_add_f32_e32 v26, v22, v17
	v_fmac_f32_e32 v20, 0xb102e308, v16
	v_sub_f32_e32 v16, v25, v21
	v_sub_f32_e32 v21, v26, v22
	v_rcp_f32_e32 v22, v26
	v_add_f32_e32 v27, v24, v20
	v_sub_f32_e32 v17, v17, v21
	v_sub_f32_e32 v21, v27, v24
	v_sub_f32_e32 v20, v20, v21
	v_mul_f32_e32 v21, v25, v22
	v_sub_f32_e32 v16, v23, v16
	v_mul_f32_e32 v23, v26, v21
	v_fma_f32 v24, v21, v26, -v23
	v_fmac_f32_e32 v24, v21, v17
	v_add_f32_e32 v10, v23, v24
	v_sub_f32_e32 v11, v25, v10
	v_sub_f32_e32 v23, v10, v23
	v_sub_f32_e32 v25, v25, v11
	v_sub_f32_e32 v23, v23, v24
	v_sub_f32_e32 v24, v25, v10
	v_add_f32_e32 v16, v16, v24
	v_add_f32_e32 v16, v23, v16
	v_add_f32_e32 v23, v11, v16
	v_mul_f32_e32 v24, v22, v23
	v_sub_f32_e32 v25, v11, v23
	v_mul_f32_e32 v10, v26, v24
	v_add_f32_e32 v16, v16, v25
	v_add_f32_e32 v25, v21, v24
	v_fma_f32 v26, v24, v26, -v10
	v_sub_f32_e32 v21, v25, v21
	v_fmac_f32_e32 v26, v24, v17
	v_sub_f32_e32 v17, v24, v21
	v_add_f32_e32 v21, v10, v26
	v_sub_f32_e32 v24, v21, v10
	v_sub_f32_e32 v10, v23, v21
	v_sub_f32_e32 v23, v23, v10
	v_sub_f32_e32 v21, v23, v21
	v_sub_f32_e32 v24, v24, v26
	v_add_f32_e32 v16, v16, v21
	v_add_f32_e32 v16, v24, v16
	v_add_f32_e32 v16, v10, v16
	v_mul_f32_e32 v16, v22, v16
	v_add_f32_e32 v16, v17, v16
	v_add_f32_e32 v17, v25, v16
	v_mul_f32_e32 v21, v17, v17
	v_fmamk_f32 v24, v21, 0x3e9b6dac, v100
	v_sub_f32_e32 v22, v17, v25
	v_ldexp_f32 v23, v17, 1
	v_mul_f32_e32 v17, v17, v21
	v_fmaak_f32 v21, v21, v24, 0x3f2aaada
	v_mul_f32_e32 v17, v17, v21
	v_add_f32_e32 v21, v23, v17
	v_sub_f32_e32 v16, v16, v22
	v_sub_f32_e32 v22, v21, v23
	v_ldexp_f32 v16, v16, 1
	v_sub_f32_e32 v17, v17, v22
	v_add_f32_e32 v16, v16, v17
	v_add_f32_e32 v17, v21, v16
	v_sub_f32_e32 v21, v17, v21
	v_add_f32_e32 v22, v27, v17
	v_sub_f32_e32 v16, v16, v21
	v_sub_f32_e32 v21, v22, v27
	v_sub_f32_e32 v23, v22, v21
	v_sub_f32_e32 v17, v17, v21
	v_add_f32_e32 v21, v20, v16
	v_sub_f32_e32 v23, v27, v23
	v_sub_f32_e32 v24, v21, v20
	v_add_f32_e32 v17, v17, v23
	v_sub_f32_e32 v23, v21, v24
	v_sub_f32_e32 v16, v16, v24
	v_sub_f32_e32 v20, v20, v23
	v_add_f32_e32 v17, v21, v17
	v_add_f32_e32 v16, v16, v20
	v_add_f32_e32 v20, v22, v17
	v_sub_f32_e32 v21, v20, v22
	v_sub_f32_e32 v17, v17, v21
	v_add_f32_e32 v16, v16, v17
	v_add_f32_e32 v16, v20, v16
	v_cmp_neq_f32_e32 vcc, s62, v18
	v_add_u32_e32 v17, -2, v108
	v_add_f32_e32 v12, v181, v183
	v_cndmask_b32_e32 v16, v105, v16, vcc
	v_cmp_ngt_f32_e32 vcc, -1.0, v18
	s_nop 1
	v_cndmask_b32_e32 v16, v106, v16, vcc
	v_cmp_neq_f32_e32 vcc, -1.0, v18
	s_nop 1
	v_cndmask_b32_e32 v16, v107, v16, vcc
	v_cmp_lt_f32_e64 vcc, |v18|, s63
	s_nop 1
	v_cndmask_b32_e32 v16, v16, v18, vcc
	v_sub_f32_e32 v16, v19, v16
	ds_bpermute_b32 v15, v15, v16
	v_cmp_lt_i32_e32 vcc, v17, v14
	v_add_u32_e32 v18, 64, v14
	s_waitcnt lgkmcnt(0)
	v_add_f32_e32 v15, v16, v15
	v_cndmask_b32_e32 v17, v17, v108, vcc
	v_lshlrev_b32_e32 v17, 2, v17
	v_cndmask_b32_e64 v15, v15, v16, s[20:21]
	ds_bpermute_b32 v16, v17, v15
	v_add_u32_e32 v17, -4, v108
	v_cmp_lt_i32_e32 vcc, v17, v14
	s_waitcnt lgkmcnt(0)
	v_add_f32_e32 v16, v15, v16
	v_cndmask_b32_e32 v17, v17, v108, vcc
	v_lshlrev_b32_e32 v17, 2, v17
	v_cndmask_b32_e64 v15, v16, v15, s[4:5]
	ds_bpermute_b32 v16, v17, v15
	v_add_u32_e32 v17, -8, v108
	v_cmp_lt_i32_e32 vcc, v17, v14
	s_waitcnt lgkmcnt(0)
	v_add_f32_e32 v16, v15, v16
	v_cndmask_b32_e32 v17, v17, v108, vcc
	v_lshlrev_b32_e32 v17, 2, v17
	v_cndmask_b32_e64 v15, v16, v15, s[6:7]
	ds_bpermute_b32 v16, v17, v15
	v_add_u32_e32 v17, -16, v108
	v_cmp_lt_i32_e32 vcc, v17, v14
	s_waitcnt lgkmcnt(0)
	v_add_f32_e32 v16, v15, v16
	v_cndmask_b32_e32 v17, v17, v108, vcc
	v_lshlrev_b32_e32 v17, 2, v17
	v_cndmask_b32_e64 v15, v16, v15, s[8:9]
	ds_bpermute_b32 v16, v17, v15
	v_subrev_u32_e32 v17, 32, v108
	v_cmp_lt_i32_e32 vcc, v17, v14
	s_waitcnt lgkmcnt(0)
	v_add_f32_e32 v16, v15, v16
	v_cndmask_b32_e32 v17, v17, v108, vcc
	v_lshlrev_b32_e32 v17, 2, v17
	v_cndmask_b32_e64 v15, v16, v15, s[10:11]
	ds_bpermute_b32 v16, v17, v15
	v_xor_b32_e32 v17, 1, v108
	v_cmp_lt_i32_e32 vcc, v17, v18
	s_waitcnt lgkmcnt(0)
	v_add_f32_e32 v14, v15, v16
	v_cndmask_b32_e64 v15, v14, v15, s[12:13]
	ds_bpermute_b32 v14, v109, v15
	v_cndmask_b32_e32 v16, v108, v17, vcc
	v_lshlrev_b32_e32 v16, 2, v16
	s_waitcnt lgkmcnt(0)
	v_sub_f32_e32 v13, v14, v15
	v_add_f32_e32 v13, v12, v13
	ds_bpermute_b32 v12, v16, v13
	v_xor_b32_e32 v15, 2, v108
	v_cmp_lt_i32_e32 vcc, v15, v18
	v_xor_b32_e32 v16, 4, v108
	s_waitcnt lgkmcnt(0)
	v_max_f32_e32 v12, v12, v12
	v_cndmask_b32_e32 v15, v108, v15, vcc
	v_lshlrev_b32_e32 v15, 2, v15
	v_max_f32_e32 v12, v13, v12
	ds_bpermute_b32 v15, v15, v12
	v_cmp_lt_i32_e32 vcc, v16, v18
	s_waitcnt lgkmcnt(0)
	v_max_f32_e32 v15, v15, v15
	v_cndmask_b32_e32 v16, v108, v16, vcc
	v_lshlrev_b32_e32 v16, 2, v16
	v_max_f32_e32 v12, v12, v15
	ds_bpermute_b32 v15, v16, v12
	v_xor_b32_e32 v16, 8, v108
	v_cmp_lt_i32_e32 vcc, v16, v18
	s_waitcnt lgkmcnt(0)
	v_max_f32_e32 v15, v15, v15
	v_cndmask_b32_e32 v16, v108, v16, vcc
	v_lshlrev_b32_e32 v16, 2, v16
	v_max_f32_e32 v12, v12, v15
	ds_bpermute_b32 v15, v16, v12
	v_xor_b32_e32 v16, 16, v108
	v_cmp_lt_i32_e32 vcc, v16, v18
	s_waitcnt lgkmcnt(0)
	v_max_f32_e32 v15, v15, v15
	v_cndmask_b32_e32 v16, v108, v16, vcc
	v_lshlrev_b32_e32 v16, 2, v16
	v_max_f32_e32 v12, v12, v15
	ds_bpermute_b32 v15, v16, v12
	v_xor_b32_e32 v16, 32, v108
	v_cmp_lt_i32_e32 vcc, v16, v18
	s_waitcnt lgkmcnt(0)
	v_max_f32_e32 v15, v15, v15
	v_cndmask_b32_e32 v16, v108, v16, vcc
	v_max_f32_e32 v12, v12, v15
	v_lshlrev_b32_e32 v15, 2, v16
	ds_bpermute_b32 v15, v15, v12
	s_waitcnt lgkmcnt(0)
	v_max_f32_e32 v15, v15, v15
	v_max_f32_e32 v12, v12, v15
	v_sub_f32_e32 v13, v13, v12
	v_mul_f32_e32 v13, 0x3fb8aa3b, v13
	v_exp_f32_e32 v13, v13
	ds_write_b32 v91, v13 offset:51200
	v_mov_b32_e32 v234, v12
	v_mov_b32_e32 v235, v14
.LBB0_289:
	s_or_b64 exec, exec, s[46:47]
	ds_write_b128 v101, v[168:171] offset:25600
	ds_write_b128 v102, v[172:175] offset:25600
	ds_write_b128 v103, v[176:179] offset:25600
	s_add_i32 s34, s42, s90
	s_cmpk_gt_i32 s34, 0x7ff
	s_cbranch_scc1 .Lp2_pf1_none
	s_ashr_i32 s44, s34, 8
	s_lshl_b32 s45, s34, 6
	s_lshl_b32 s44, s44, 12
	s_and_b32 s65, s45, 0xfc0
	s_or_b32 s48, s44, s65
	s_bfe_u32 s43, s34, 0x20006
	s_mul_i32 s72, s43, 0xc0
	s_lshl_b32 s45, s72, 1
	s_lshl_b32 s43, s43, 2
	v_add_u32_e32 v196, s48, v70
	v_add_u32_e32 v197, s48, v74
	v_add_u32_e32 v198, s48, v78
	v_mul_lo_u32 v196, v196, s54
	v_mul_lo_u32 v197, v197, s54
	v_mul_lo_u32 v198, v198, s54
	v_lshl_add_u32 v196, v72, 1, v196
	v_lshl_add_u32 v197, v76, 1, v197
	v_lshl_add_u32 v198, v80, 1, v198
	v_add_u32_e32 v196, s45, v196
	v_add_u32_e32 v197, s45, v197
	v_add_u32_e32 v198, s45, v198
	global_load_dwordx4 v[168:171], v196, s[60:61] offset:3072
	global_load_dwordx4 v[172:175], v197, s[60:61] offset:3072
	global_load_dwordx4 v[176:179], v198, s[60:61] offset:3072
	s_and_saveexec_b64 s[46:47], s[0:1]
	s_cbranch_execz .Lp2_pf_g_b
	v_add_u32_e32 v199, s48, v68
	v_lshlrev_b32_e32 v199, 5, v199
	v_add_u32_e32 v199, s43, v199
	v_mov_b32_e32 v200, s43
	global_load_dword v180, v199, s[78:79] offset:16
	global_load_dword v182, v200, s[66:67] offset:16
	global_load_dword v181, v199, s[78:79]
	global_load_dword v183, v200, s[66:67]

.Lp2_pf1_none:
	s_waitcnt lgkmcnt(0)
	s_barrier
	s_and_saveexec_b64 s[46:47], s[16:17]
	s_cbranch_execz .LBB0_305
	ds_read_b128 v[236:239], v95 offset:51200
	s_cmpk_gt_i32 s34, 0x7ff
	s_cbranch_scc1 .Lp2_cw_0
	s_cmp_eq_u32 s64, 0
	s_cbranch_scc1 .Lp2_cw_a
	s_waitcnt vmcnt(3)
	s_branch .Lp2_cw_done
.Lp2_cw_a:
	s_waitcnt vmcnt(7)
	s_branch .Lp2_cw_done

.Lp2_cw_done:
	v_lshlrev_b32_e32 v110, 16, v218
	v_and_b32_e32 v111, 0xffff0000, v218
	v_lshlrev_b32_e32 v112, 16, v230
	v_and_b32_e32 v113, 0xffff0000, v230
	v_lshlrev_b32_e32 v114, 16, v226
	v_and_b32_e32 v115, 0xffff0000, v226
	v_lshlrev_b32_e32 v122, 16, v222
	v_and_b32_e32 v123, 0xffff0000, v222
	s_waitcnt lgkmcnt(0)
	v_mul_f32_e32 v24, 0x3d93cd3a, v236
	v_mul_f32_e32 v20, 0x3d93cd3a, v237
	v_mul_f32_e32 v16, 0x3d93cd3a, v238
	v_mul_f32_e32 v12, 0x3d93cd3a, v239
	v_lshlrev_b32_e32 v120, 16, v206
	v_and_b32_e32 v121, 0xffff0000, v206
	v_lshlrev_b32_e32 v116, 16, v214
	v_and_b32_e32 v117, 0xffff0000, v214
	v_lshlrev_b32_e32 v118, 16, v210
	v_and_b32_e32 v119, 0xffff0000, v210
	v_pk_fma_f32 v[120:121], v[48:49], v[120:121], v[56:57]
	v_pk_fma_f32 v[124:125], v[48:49], v[116:117], v[56:57]
	v_pk_fma_f32 v[126:127], v[48:49], v[118:119], v[56:57]
	v_pk_fma_f32 v[48:49], v[48:49], v[110:111], v[56:57]
	v_pk_fma_f32 v[118:119], v[52:53], v[118:119], v[120:121]
	v_pk_fma_f32 v[56:57], v[52:53], v[116:117], v[126:127]
	v_pk_fma_f32 v[120:121], v[52:53], v[110:111], v[124:125]
	v_pk_fma_f32 v[48:49], v[52:53], v[112:113], v[48:49]
	v_pk_fma_f32 v[52:53], v[60:61], v[116:117], v[118:119]
	v_pk_fma_f32 v[56:57], v[60:61], v[110:111], v[56:57]
	v_pk_fma_f32 v[116:117], v[60:61], v[112:113], v[120:121]
	v_pk_fma_f32 v[52:53], v[64:65], v[110:111], v[52:53]
	v_pk_fma_f32 v[48:49], v[60:61], v[114:115], v[48:49]
	v_pk_fma_f32 v[56:57], v[64:65], v[112:113], v[56:57]
	v_pk_fma_f32 v[60:61], v[64:65], v[114:115], v[116:117]
	v_mul_f32_e32 v0, 0xbfb8aa3b, v52
	v_mul_f32_e32 v4, 0xbfb8aa3b, v53
	v_pk_fma_f32 v[48:49], v[64:65], v[122:123], v[48:49]
	v_mul_f32_e32 v64, 0xbfb8aa3b, v57
	v_mul_f32_e32 v65, 0xbfb8aa3b, v60
	v_exp_f32_e32 v0, v0
	v_exp_f32_e32 v4, v4
	v_exp_f32_e32 v64, v64
	v_exp_f32_e32 v65, v65
	v_mul_f32_e32 v8, 0xbfb8aa3b, v56
	v_exp_f32_e32 v8, v8
	v_mul_f32_e32 v84, 0xbfb8aa3b, v61
	v_mul_f32_e32 v111, 0xbfb8aa3b, v49
	v_add_f32_e32 v0, 1.0, v0
	v_add_f32_e32 v4, 1.0, v4
	v_mul_f32_e32 v110, 0xbfb8aa3b, v48
	v_exp_f32_e32 v84, v84
	v_exp_f32_e32 v115, v111
	v_add_f32_e32 v111, 1.0, v64
	v_add_f32_e32 v112, 1.0, v65
	v_rcp_f32_e32 v64, v0
	v_rcp_f32_e32 v65, v4
	v_exp_f32_e32 v114, v110
	v_add_f32_e32 v8, 1.0, v8
	v_rcp_f32_e32 v110, v8
	v_rcp_f32_e32 v111, v111
	v_add_f32_e32 v84, 1.0, v84
	v_pk_mul_f32 v[52:53], v[52:53], v[64:65]
	v_rcp_f32_e32 v112, v112
	v_rcp_f32_e32 v113, v84
	v_pk_mul_f32 v[52:53], v[24:25], v[52:53] op_sel_hi:[0,1]
	v_add_f32_e32 v8, 1.0, v114
	v_cvt_pk_bf16_f32 v4, v52, v53
	v_rcp_f32_e32 v52, v8
	v_add_f32_e32 v8, 1.0, v115
	v_pk_mul_f32 v[56:57], v[56:57], v[110:111]
	v_rcp_f32_e32 v53, v8
	v_pk_mul_f32 v[56:57], v[20:21], v[56:57] op_sel_hi:[0,1]
	v_lshlrev_b32_e32 v116, 16, v207
	v_and_b32_e32 v117, 0xffff0000, v207
	v_cvt_pk_bf16_f32 v0, v56, v57
	v_pk_mul_f32 v[56:57], v[60:61], v[112:113]
	v_lshlrev_b32_e32 v112, 16, v211
	v_and_b32_e32 v113, 0xffff0000, v211
	v_pk_fma_f32 v[116:117], v[50:51], v[116:117], v[58:59]
	v_lshlrev_b32_e32 v64, 16, v215
	v_and_b32_e32 v65, 0xffff0000, v215
	v_pk_fma_f32 v[114:115], v[50:51], v[112:113], v[58:59]
	v_pk_fma_f32 v[112:113], v[54:55], v[112:113], v[116:117]
	v_pk_mul_f32 v[48:49], v[48:49], v[52:53]
	v_lshlrev_b32_e32 v52, 16, v219
	v_and_b32_e32 v53, 0xffff0000, v219
	v_pk_fma_f32 v[112:113], v[62:63], v[64:65], v[112:113]
	v_pk_mul_f32 v[56:57], v[16:17], v[56:57] op_sel_hi:[0,1]
	v_pk_fma_f32 v[112:113], v[66:67], v[52:53], v[112:113]
	v_pk_fma_f32 v[110:111], v[50:51], v[64:65], v[58:59]
	v_mul_f32_e32 v1, 0xbfb8aa3b, v112
	v_exp_f32_e32 v1, v1
	v_mul_f32_e32 v5, 0xbfb8aa3b, v113
	v_exp_f32_e32 v5, v5
	v_pk_fma_f32 v[64:65], v[54:55], v[64:65], v[114:115]
	v_cvt_pk_bf16_f32 v8, v56, v57
	v_lshlrev_b32_e32 v56, 16, v231
	v_and_b32_e32 v57, 0xffff0000, v231
	v_pk_fma_f32 v[64:65], v[62:63], v[52:53], v[64:65]
	v_add_f32_e32 v1, 1.0, v1
	v_pk_fma_f32 v[64:65], v[66:67], v[56:57], v[64:65]
	v_rcp_f32_e32 v114, v1
	v_add_f32_e32 v1, 1.0, v5
	v_mul_f32_e32 v5, 0xbfb8aa3b, v64
	v_exp_f32_e32 v5, v5
	v_mul_f32_e32 v9, 0xbfb8aa3b, v65
	v_exp_f32_e32 v9, v9
	v_pk_fma_f32 v[110:111], v[54:55], v[52:53], v[110:111]
	v_lshlrev_b32_e32 v60, 16, v227
	v_and_b32_e32 v61, 0xffff0000, v227
	v_rcp_f32_e32 v115, v1
	v_add_f32_e32 v1, 1.0, v5
	v_pk_fma_f32 v[110:111], v[62:63], v[56:57], v[110:111]
	v_rcp_f32_e32 v116, v1
	v_add_f32_e32 v1, 1.0, v9
	v_pk_fma_f32 v[110:111], v[66:67], v[60:61], v[110:111]
	v_rcp_f32_e32 v117, v1
	v_mul_f32_e32 v1, 0xbfb8aa3b, v110
	v_exp_f32_e32 v9, v1
	v_mul_f32_e32 v1, 0xbfb8aa3b, v111
	v_pk_mul_f32 v[48:49], v[12:13], v[48:49] op_sel_hi:[0,1]
	v_pk_mul_f32 v[112:113], v[112:113], v[114:115]
	v_exp_f32_e32 v13, v1
	v_pk_fma_f32 v[50:51], v[50:51], v[52:53], v[58:59]
	v_pk_mul_f32 v[112:113], v[24:25], v[112:113] op_sel_hi:[0,1]
	v_pk_fma_f32 v[50:51], v[54:55], v[56:57], v[50:51]
	v_cvt_pk_bf16_f32 v5, v112, v113
	v_pk_mul_f32 v[64:65], v[64:65], v[116:117]
	v_lshlrev_b32_e32 v112, 16, v223
	v_and_b32_e32 v113, 0xffff0000, v223
	v_pk_fma_f32 v[50:51], v[62:63], v[60:61], v[50:51]
	v_pk_mul_f32 v[64:65], v[20:21], v[64:65] op_sel_hi:[0,1]
	v_add_f32_e32 v9, 1.0, v9
	v_pk_fma_f32 v[50:51], v[66:67], v[112:113], v[50:51]
	v_cvt_pk_bf16_f32 v1, v64, v65
	v_rcp_f32_e32 v64, v9
	v_add_f32_e32 v9, 1.0, v13
	v_mul_f32_e32 v13, 0xbfb8aa3b, v50
	v_exp_f32_e32 v13, v13
	v_mul_f32_e32 v17, 0xbfb8aa3b, v51
	v_exp_f32_e32 v17, v17
	v_rcp_f32_e32 v65, v9
	v_add_f32_e32 v9, 1.0, v13
	v_rcp_f32_e32 v52, v9
	v_add_f32_e32 v9, 1.0, v17
	v_rcp_f32_e32 v53, v9
	v_lshlrev_b32_e32 v66, 16, v208
	v_and_b32_e32 v67, 0xffff0000, v208
	v_lshlrev_b32_e32 v62, 16, v212
	v_and_b32_e32 v63, 0xffff0000, v212
	v_pk_fma_f32 v[66:67], v[28:29], v[66:67], v[32:33]
	v_pk_mul_f32 v[54:55], v[110:111], v[64:65]
	v_lshlrev_b32_e32 v58, 16, v216
	v_and_b32_e32 v59, 0xffff0000, v216
	v_pk_fma_f32 v[64:65], v[28:29], v[62:63], v[32:33]
	v_pk_fma_f32 v[62:63], v[36:37], v[62:63], v[66:67]
	v_pk_mul_f32 v[50:51], v[50:51], v[52:53]
	v_lshlrev_b32_e32 v52, 16, v220
	v_and_b32_e32 v53, 0xffff0000, v220
	v_pk_fma_f32 v[62:63], v[40:41], v[58:59], v[62:63]
	v_pk_mul_f32 v[54:55], v[16:17], v[54:55] op_sel_hi:[0,1]
	v_pk_fma_f32 v[62:63], v[44:45], v[52:53], v[62:63]
	v_pk_fma_f32 v[60:61], v[28:29], v[58:59], v[32:33]
	v_mul_f32_e32 v2, 0xbfb8aa3b, v62
	v_exp_f32_e32 v2, v2
	v_mul_f32_e32 v6, 0xbfb8aa3b, v63
	v_exp_f32_e32 v6, v6
	v_pk_fma_f32 v[58:59], v[36:37], v[58:59], v[64:65]
	v_cvt_pk_bf16_f32 v9, v54, v55
	v_lshlrev_b32_e32 v54, 16, v232
	v_and_b32_e32 v55, 0xffff0000, v232
	v_pk_fma_f32 v[58:59], v[40:41], v[52:53], v[58:59]
	v_add_f32_e32 v2, 1.0, v2
	v_pk_fma_f32 v[58:59], v[44:45], v[54:55], v[58:59]
	v_rcp_f32_e32 v64, v2
	v_add_f32_e32 v2, 1.0, v6
	v_mul_f32_e32 v6, 0xbfb8aa3b, v58
	v_exp_f32_e32 v6, v6
	v_mul_f32_e32 v10, 0xbfb8aa3b, v59
	v_exp_f32_e32 v10, v10
	v_pk_fma_f32 v[60:61], v[36:37], v[52:53], v[60:61]
	v_lshlrev_b32_e32 v56, 16, v228
	v_and_b32_e32 v57, 0xffff0000, v228
	v_rcp_f32_e32 v65, v2
	v_add_f32_e32 v2, 1.0, v6
	v_pk_fma_f32 v[60:61], v[40:41], v[54:55], v[60:61]
	v_rcp_f32_e32 v66, v2
	v_add_f32_e32 v2, 1.0, v10
	v_pk_fma_f32 v[60:61], v[44:45], v[56:57], v[60:61]
	v_rcp_f32_e32 v67, v2
	v_mul_f32_e32 v2, 0xbfb8aa3b, v60
	v_exp_f32_e32 v10, v2
	v_mul_f32_e32 v2, 0xbfb8aa3b, v61
	v_pk_mul_f32 v[50:51], v[12:13], v[50:51] op_sel_hi:[0,1]
	v_pk_mul_f32 v[62:63], v[62:63], v[64:65]
	v_exp_f32_e32 v13, v2
	v_pk_fma_f32 v[28:29], v[28:29], v[52:53], v[32:33]
	v_pk_mul_f32 v[62:63], v[24:25], v[62:63] op_sel_hi:[0,1]
	v_pk_fma_f32 v[28:29], v[36:37], v[54:55], v[28:29]
	v_cvt_pk_bf16_f32 v6, v62, v63
	v_pk_mul_f32 v[58:59], v[58:59], v[66:67]
	v_lshlrev_b32_e32 v62, 16, v224
	v_and_b32_e32 v63, 0xffff0000, v224
	v_pk_fma_f32 v[28:29], v[40:41], v[56:57], v[28:29]
	v_pk_mul_f32 v[58:59], v[20:21], v[58:59] op_sel_hi:[0,1]
	v_add_f32_e32 v10, 1.0, v10
	v_pk_fma_f32 v[28:29], v[44:45], v[62:63], v[28:29]
	v_cvt_pk_bf16_f32 v2, v58, v59
	v_rcp_f32_e32 v58, v10
	v_add_f32_e32 v10, 1.0, v13
	v_mul_f32_e32 v13, 0xbfb8aa3b, v28
	v_exp_f32_e32 v13, v13
	v_mul_f32_e32 v14, 0xbfb8aa3b, v29
	v_exp_f32_e32 v14, v14
	v_rcp_f32_e32 v59, v10
	v_add_f32_e32 v10, 1.0, v13
	v_rcp_f32_e32 v32, v10
	v_add_f32_e32 v10, 1.0, v14
	v_rcp_f32_e32 v33, v10
	v_lshlrev_b32_e32 v52, 16, v209
	v_and_b32_e32 v53, 0xffff0000, v209
	v_lshlrev_b32_e32 v40, 16, v213
	v_and_b32_e32 v41, 0xffff0000, v213
	v_pk_fma_f32 v[52:53], v[30:31], v[52:53], v[34:35]
	v_pk_mul_f32 v[28:29], v[28:29], v[32:33]
	v_lshlrev_b32_e32 v32, 16, v217
	v_and_b32_e32 v33, 0xffff0000, v217
	v_pk_fma_f32 v[44:45], v[30:31], v[40:41], v[34:35]
	v_pk_fma_f32 v[40:41], v[38:39], v[40:41], v[52:53]
	v_lshlrev_b32_e32 v14, 16, v221
	v_and_b32_e32 v15, 0xffff0000, v221
	v_pk_fma_f32 v[40:41], v[42:43], v[32:33], v[40:41]
	v_pk_mul_f32 v[36:37], v[60:61], v[58:59]
	v_pk_fma_f32 v[40:41], v[46:47], v[14:15], v[40:41]
	v_pk_mul_f32 v[36:37], v[16:17], v[36:37] op_sel_hi:[0,1]
	v_mul_f32_e32 v3, 0xbfb8aa3b, v40
	v_exp_f32_e32 v3, v3
	v_mul_f32_e32 v7, 0xbfb8aa3b, v41
	v_exp_f32_e32 v7, v7
	v_cvt_pk_bf16_f32 v10, v36, v37
	v_pk_fma_f32 v[36:37], v[30:31], v[32:33], v[34:35]
	v_pk_fma_f32 v[32:33], v[38:39], v[32:33], v[44:45]
	v_lshlrev_b32_e32 v26, 16, v233
	v_and_b32_e32 v27, 0xffff0000, v233
	v_pk_fma_f32 v[32:33], v[42:43], v[14:15], v[32:33]
	v_add_f32_e32 v3, 1.0, v3
	v_pk_fma_f32 v[32:33], v[46:47], v[26:27], v[32:33]
	v_rcp_f32_e32 v44, v3
	v_add_f32_e32 v3, 1.0, v7
	v_mul_f32_e32 v7, 0xbfb8aa3b, v32
	v_exp_f32_e32 v7, v7
	v_mul_f32_e32 v11, 0xbfb8aa3b, v33
	v_exp_f32_e32 v11, v11
	v_rcp_f32_e32 v45, v3
	v_add_f32_e32 v3, 1.0, v7
	v_rcp_f32_e32 v52, v3
	v_add_f32_e32 v3, 1.0, v11
	v_rcp_f32_e32 v53, v3
	v_pk_mul_f32 v[40:41], v[40:41], v[44:45]
	v_lshlrev_b32_e32 v22, 16, v229
	v_pk_mul_f32 v[24:25], v[24:25], v[40:41] op_sel_hi:[0,1]
	v_cvt_pk_bf16_f32 v7, v24, v25
	v_pk_mul_f32 v[24:25], v[32:33], v[52:53]
	v_and_b32_e32 v23, 0xffff0000, v229
	v_pk_mul_f32 v[20:21], v[20:21], v[24:25] op_sel_hi:[0,1]
	v_pk_fma_f32 v[24:25], v[38:39], v[14:15], v[36:37]
	v_pk_mul_f32 v[28:29], v[12:13], v[28:29] op_sel_hi:[0,1]
	v_pk_fma_f32 v[24:25], v[42:43], v[26:27], v[24:25]
	v_pk_fma_f32 v[14:15], v[30:31], v[14:15], v[34:35]
	v_pk_fma_f32 v[24:25], v[46:47], v[22:23], v[24:25]
	v_pk_fma_f32 v[14:15], v[38:39], v[26:27], v[14:15]
	v_mul_f32_e32 v3, 0xbfb8aa3b, v24
	v_exp_f32_e32 v11, v3
	v_mul_f32_e32 v3, 0xbfb8aa3b, v25
	v_exp_f32_e32 v13, v3
	v_cvt_pk_bf16_f32 v3, v20, v21
	v_lshlrev_b32_e32 v20, 16, v225
	v_and_b32_e32 v21, 0xffff0000, v225
	v_pk_fma_f32 v[14:15], v[42:43], v[22:23], v[14:15]
	v_add_f32_e32 v11, 1.0, v11
	v_pk_fma_f32 v[14:15], v[46:47], v[20:21], v[14:15]
	v_rcp_f32_e32 v18, v11
	v_add_f32_e32 v11, 1.0, v13
	v_mul_f32_e32 v13, 0xbfb8aa3b, v14
	v_exp_f32_e32 v13, v13
	v_mul_f32_e32 v17, 0xbfb8aa3b, v15
	v_exp_f32_e32 v17, v17
	v_rcp_f32_e32 v19, v11
	v_add_f32_e32 v11, 1.0, v13
	v_rcp_f32_e32 v20, v11
	v_add_f32_e32 v11, 1.0, v17
	v_rcp_f32_e32 v21, v11
	v_pk_mul_f32 v[18:19], v[24:25], v[18:19]
	v_pk_mul_f32 v[14:15], v[14:15], v[20:21]
	v_pk_mul_f32 v[16:17], v[16:17], v[18:19] op_sel_hi:[0,1]
	v_cvt_pk_bf16_f32 v11, v16, v17
	v_pk_mul_f32 v[16:17], v[12:13], v[14:15] op_sel_hi:[0,1]
	v_cvt_pk_bf16_f32 v12, v48, v49
	v_cvt_pk_bf16_f32 v13, v50, v51
	v_cvt_pk_bf16_f32 v14, v28, v29
	v_cvt_pk_bf16_f32 v15, v16, v17
	ds_write_b128 v104, v[4:7]
	ds_write_b128 v104, v[0:3] offset:400
	ds_write_b128 v104, v[8:11] offset:800
	ds_write_b128 v104, v[12:15] offset:1200
.LBB0_305:
	s_or_b64 exec, exec, s[46:47]
	s_and_saveexec_b64 s[46:47], s[14:15]
	s_cbranch_execz .Lp2_ml_skip
	s_ashr_i32 s43, s42, 31
	s_lshl_b64 s[48:49], s[42:43], 2
	s_add_u32 s76, s50, s48
	s_addc_u32 s77, s51, s49
	s_add_u32 s48, s52, s48
	s_addc_u32 s49, s53, s49
	global_store_dword v85, v234, s[76:77]
	global_store_dword v85, v235, s[48:49]
.Lp2_ml_skip:
	s_or_b64 exec, exec, s[46:47]
	s_add_i32 s34, s42, s90
	s_cmpk_gt_i32 s34, 0x7ff
	s_cbranch_scc1 .Lp2_pf_none
	s_and_saveexec_b64 s[46:47], s[16:17]
	s_cbranch_execz .Lp2_pf_r_b
	v_add_u32_e32 v199, s72, v94
	v_add_u32_e32 v200, s65, v92
	v_cmp_ne_u32_e32 vcc, 0, v200
	v_add_u32_e32 v201, s44, v200
	v_mul_lo_u32 v201, v201, s54
	v_lshl_add_u32 v201, v199, 1, v201
	v_lshlrev_b32_e32 v189, 2, v199
	v_add_u32_e32 v193, 0x1800, v189
	v_add_u32_e32 v194, 0x3000, v189
	v_add_u32_e32 v195, 0x4800, v189
	v_add_u32_e32 v196, 0xffffac00, v201
	v_add_u32_e32 v197, 0xffffc800, v201
	v_add_u32_e32 v198, 0xffffe400, v201
	v_add_u32_e32 v202, 0x1c00, v201
	v_add_u32_e32 v203, 0x3800, v201
	v_add_u32_e32 v200, 0x5400, v201
	v_mov_b32_e32 v206, 0
	v_mov_b32_e32 v207, 0
	v_mov_b32_e32 v208, 0
	v_mov_b32_e32 v209, 0
	v_mov_b32_e32 v210, 0
	v_mov_b32_e32 v211, 0
	v_mov_b32_e32 v212, 0
	v_mov_b32_e32 v213, 0
	v_mov_b32_e32 v214, 0
	v_mov_b32_e32 v215, 0
	v_mov_b32_e32 v216, 0
	v_mov_b32_e32 v217, 0
	s_and_b64 exec, exec, vcc
	global_load_dwordx4 v[206:209], v196, s[60:61]
	global_load_dwordx4 v[210:213], v197, s[60:61]
	global_load_dwordx4 v[214:217], v198, s[60:61]
	s_mov_b64 exec, s[16:17]
	global_load_dwordx4 v[218:221], v201, s[60:61]
	global_load_dwordx4 v[230:233], v202, s[60:61]
	global_load_dwordx4 v[226:229], v203, s[60:61]
	global_load_dwordx4 v[222:225], v200, s[60:61]

.Lp2_pf_none:
	s_bfe_u32 s46, s64, 0x20006
	s_ashr_i32 s44, s64, 8
	s_mul_i32 s43, s46, 3
	s_mul_i32 s34, s46, 0x60
	v_add_u32_e32 v28, s34, v96
	s_add_i32 s34, s43, 1
	s_mul_i32 s45, s44, 0xc0
	s_add_i32 s43, s43, 2
	v_lshl_add_u32 v36, s34, 5, v96
	v_add_u32_e32 v84, s45, v96
	v_lshl_add_u32 v48, s43, 5, v96
	s_waitcnt lgkmcnt(0)
	s_barrier
	ds_read_b64_tr_b16 v[0:1], v28 offset:25600
	ds_read_b64_tr_b16 v[2:3], v28 offset:27200
	ds_read_b64_tr_b16 v[6:7], v84 offset:1600
	ds_read_b64_tr_b16 v[4:5], v84
	ds_read_b64_tr_b16 v[8:9], v36 offset:25600
	ds_read_b64_tr_b16 v[10:11], v36 offset:27200
	ds_read_b64_tr_b16 v[12:13], v84 offset:32
	ds_read_b64_tr_b16 v[16:17], v84 offset:64
	ds_read_b64_tr_b16 v[20:21], v84 offset:96
	ds_read_b64_tr_b16 v[14:15], v84 offset:1632
	ds_read_b64_tr_b16 v[24:25], v84 offset:160
	ds_read_b64_tr_b16 v[30:31], v28 offset:40000
	ds_read_b64_tr_b16 v[38:39], v36 offset:40000
	ds_read_b64_tr_b16 v[44:45], v48 offset:25600
	ds_read_b64_tr_b16 v[46:47], v48 offset:27200
	ds_read_b64_tr_b16 v[50:51], v48 offset:40000
	ds_read_b64_tr_b16 v[18:19], v84 offset:1664
	ds_read_b64_tr_b16 v[22:23], v84 offset:1696
	ds_read_b64_tr_b16 v[62:63], v84 offset:1728
	ds_read_b64_tr_b16 v[26:27], v84 offset:1760
	ds_read_b64_tr_b16 v[60:61], v84 offset:128
	ds_read_b64_tr_b16 v[28:29], v28 offset:38400
	ds_read_b64_tr_b16 v[36:37], v36 offset:38400
	ds_read_b64_tr_b16 v[48:49], v48 offset:38400
	s_waitcnt lgkmcnt(14)
	v_mfma_f32_16x16x32_bf16 v[32:35], v[4:7], v[0:3], 0
	ds_read_b64_tr_b16 v[130:131], v84 offset:12800
	ds_read_b64_tr_b16 v[134:135], v84 offset:12832
	ds_read_b64_tr_b16 v[138:139], v84 offset:12864
	ds_read_b64_tr_b16 v[142:143], v84 offset:12896
	ds_read_b64_tr_b16 v[132:133], v84 offset:14400
	ds_read_b64_tr_b16 v[136:137], v84 offset:14432
	ds_read_b64_tr_b16 v[146:147], v84 offset:12928
	ds_read_b64_tr_b16 v[150:151], v84 offset:12960
	s_mul_i32 s46, s46, 48
	v_mfma_f32_16x16x32_bf16 v[40:43], v[4:7], v[8:11], 0
	s_mul_i32 s47, s44, 6
	ds_read_b64_tr_b16 v[140:141], v84 offset:14464
	ds_read_b64_tr_b16 v[144:145], v84 offset:14496
	ds_read_b64_tr_b16 v[148:149], v84 offset:14528
	ds_read_b64_tr_b16 v[152:153], v84 offset:14560
	v_or_b32_e32 v84, s47, v97
	s_waitcnt lgkmcnt(14)
	v_mfma_f32_16x16x32_bf16 v[4:7], v[4:7], v[44:47], 0
	s_mul_i32 s44, s42, 0x12000
	v_lshlrev_b32_e32 v84, 4, v84
	s_mul_hi_i32 s45, s42, 0x12000
	v_mfma_f32_16x16x32_bf16 v[52:55], v[12:15], v[0:3], 0
	s_add_u32 s44, s26, s44
	s_addc_u32 s45, s27, s45
	v_mfma_f32_16x16x32_bf16 v[56:59], v[12:15], v[8:11], 0
	v_mfma_f32_16x16x32_bf16 v[12:15], v[12:15], v[44:47], 0
	v_mfma_f32_16x16x32_bf16 v[64:67], v[16:19], v[0:3], 0
	v_mfma_f32_16x16x32_bf16 v[110:113], v[16:19], v[8:11], 0
	v_mfma_f32_16x16x32_bf16 v[16:19], v[16:19], v[44:47], 0
	v_mfma_f32_16x16x32_bf16 v[114:117], v[20:23], v[0:3], 0
	v_mfma_f32_16x16x32_bf16 v[118:121], v[20:23], v[8:11], 0
	v_mfma_f32_16x16x32_bf16 v[20:23], v[20:23], v[44:47], 0
	v_mfma_f32_16x16x32_bf16 v[122:125], v[60:63], v[0:3], 0
	v_mfma_f32_16x16x32_bf16 v[126:129], v[60:63], v[8:11], 0
	v_mfma_f32_16x16x32_bf16 v[60:63], v[60:63], v[44:47], 0
	v_mfma_f32_16x16x32_bf16 v[0:3], v[24:27], v[0:3], 0
	v_mfma_f32_16x16x32_bf16 v[8:11], v[24:27], v[8:11], 0
	v_mfma_f32_16x16x32_bf16 v[24:27], v[24:27], v[44:47], 0
	v_or_b32_e32 v44, s46, v90
	v_mul_u32_u24_e32 v44, 0xc0, v44
	s_waitcnt lgkmcnt(7)
	v_mfma_f32_16x16x32_bf16 v[32:35], v[130:133], v[28:31], v[32:35]
	v_mfma_f32_16x16x32_bf16 v[40:43], v[130:133], v[36:39], v[40:43]
	v_mfma_f32_16x16x32_bf16 v[4:7], v[130:133], v[48:51], v[4:7]
	v_or_b32_e32 v130, v44, v98
	s_nop 4
	v_cvt_pk_bf16_f32 v32, v32, v33
	v_cvt_pk_bf16_f32 v33, v34, v35
	s_waitcnt lgkmcnt(6)
	v_mfma_f32_16x16x32_bf16 v[44:47], v[134:137], v[28:31], v[52:55]
	v_cvt_pk_bf16_f32 v40, v40, v41
	v_cvt_pk_bf16_f32 v41, v42, v43
	s_waitcnt lgkmcnt(3)
	v_mfma_f32_16x16x32_bf16 v[52:55], v[138:141], v[28:31], v[64:67]
	s_nop 2
	v_add_u32_e32 v66, 32, v84
	v_cvt_pk_bf16_f32 v34, v44, v45
	v_cvt_pk_bf16_f32 v35, v46, v47
	v_mfma_f32_16x16x32_bf16 v[44:47], v[134:137], v[36:39], v[56:59]
	v_permlane16_swap_b32_e32 v32, v34
	v_permlane16_swap_b32_e32 v33, v35
	s_nop 0
	v_add_u32_e32 v56, v130, v84
	v_ashrrev_i32_e32 v57, 31, v56
	v_lshl_add_u64 v[56:57], v[56:57], 1, s[44:45]
	global_store_dwordx4 v[56:57], v[32:35], off
	s_waitcnt lgkmcnt(2)
	v_mfma_f32_16x16x32_bf16 v[56:59], v[142:145], v[28:31], v[114:117]
	v_add_u32_e32 v64, v130, v66
	v_cvt_pk_bf16_f32 v32, v52, v53
	v_cvt_pk_bf16_f32 v33, v54, v55
	v_ashrrev_i32_e32 v65, 31, v64
	s_waitcnt lgkmcnt(0)
	v_mfma_f32_16x16x32_bf16 v[0:3], v[150:153], v[28:31], v[0:3]
	s_nop 1
	v_cvt_pk_bf16_f32 v34, v56, v57
	v_cvt_pk_bf16_f32 v35, v58, v59
	s_nop 0
	v_permlane16_swap_b32_e32 v32, v34
	v_mfma_f32_16x16x32_bf16 v[56:59], v[146:149], v[28:31], v[122:125]
	v_permlane16_swap_b32_e32 v33, v35
	v_lshl_add_u64 v[64:65], v[64:65], 1, s[44:45]
	global_store_dwordx4 v[64:65], v[32:35], off
	v_mfma_f32_16x16x32_bf16 v[52:55], v[138:141], v[36:39], v[110:113]
	v_cvt_pk_bf16_f32 v42, v44, v45
	s_nop 2
	v_cvt_pk_bf16_f32 v33, v58, v59
	v_add_u32_e32 v58, 64, v84
	v_cvt_pk_bf16_f32 v32, v56, v57
	v_add_u32_e32 v56, v130, v58
	v_cvt_pk_bf16_f32 v34, v0, v1
	v_cvt_pk_bf16_f32 v35, v2, v3
	v_ashrrev_i32_e32 v57, 31, v56
	v_permlane16_swap_b32_e32 v32, v34
	v_permlane16_swap_b32_e32 v33, v35
	v_lshl_add_u64 v[56:57], v[56:57], 1, s[44:45]
	global_store_dwordx4 v[56:57], v[32:35], off
	v_lshl_or_b32 v56, s34, 4, v90
	v_mfma_f32_16x16x32_bf16 v[0:3], v[142:145], v[36:39], v[118:121]
	v_mul_u32_u24_e32 v56, 0xc0, v56
	v_or_b32_e32 v56, v56, v98
	v_cvt_pk_bf16_f32 v43, v46, v47
	v_mfma_f32_16x16x32_bf16 v[28:31], v[146:149], v[36:39], v[126:129]
	v_permlane16_swap_b32_e32 v40, v42
	v_permlane16_swap_b32_e32 v41, v43
	v_mfma_f32_16x16x32_bf16 v[8:11], v[150:153], v[36:39], v[8:11]
	v_add_u32_e32 v36, v56, v84
	v_ashrrev_i32_e32 v37, 31, v36
	v_lshl_add_u64 v[36:37], v[36:37], 1, s[44:45]
	v_cvt_pk_bf16_f32 v38, v0, v1
	v_add_u32_e32 v0, v56, v66
	global_store_dwordx4 v[36:37], v[40:43], off
	v_cvt_pk_bf16_f32 v36, v52, v53
	v_cvt_pk_bf16_f32 v37, v54, v55
	v_cvt_pk_bf16_f32 v39, v2, v3
	v_ashrrev_i32_e32 v1, 31, v0
	v_permlane16_swap_b32_e32 v36, v38
	v_permlane16_swap_b32_e32 v37, v39
	v_lshl_add_u64 v[0:1], v[0:1], 1, s[44:45]
	v_cvt_pk_bf16_f32 v2, v8, v9
	v_add_u32_e32 v8, v56, v58
	global_store_dwordx4 v[0:1], v[36:39], off
	v_cvt_pk_bf16_f32 v0, v28, v29
	v_cvt_pk_bf16_f32 v1, v30, v31
	v_cvt_pk_bf16_f32 v3, v10, v11
	v_ashrrev_i32_e32 v9, 31, v8
	v_permlane16_swap_b32_e32 v0, v2
	v_permlane16_swap_b32_e32 v1, v3
	v_lshl_add_u64 v[8:9], v[8:9], 1, s[44:45]
	v_mfma_f32_16x16x32_bf16 v[12:15], v[134:137], v[48:51], v[12:15]
	global_store_dwordx4 v[8:9], v[0:3], off
	s_nop 1
	v_lshl_or_b32 v0, s43, 4, v90
	v_mul_u32_u24_e32 v0, 0xc0, v0
	v_or_b32_e32 v8, v0, v98
	v_mfma_f32_16x16x32_bf16 v[16:19], v[138:141], v[48:51], v[16:19]
	v_cvt_pk_bf16_f32 v0, v4, v5
	v_add_u32_e32 v4, v8, v84
	v_cvt_pk_bf16_f32 v1, v6, v7
	v_mfma_f32_16x16x32_bf16 v[20:23], v[142:145], v[48:51], v[20:23]
	v_cvt_pk_bf16_f32 v2, v12, v13
	v_cvt_pk_bf16_f32 v3, v14, v15
	v_ashrrev_i32_e32 v5, 31, v4
	v_permlane16_swap_b32_e32 v0, v2
	v_permlane16_swap_b32_e32 v1, v3
	v_lshl_add_u64 v[4:5], v[4:5], 1, s[44:45]
	v_mfma_f32_16x16x32_bf16 v[32:35], v[146:149], v[48:51], v[60:63]
	global_store_dwordx4 v[4:5], v[0:3], off
	v_add_u32_e32 v4, v8, v66
	v_ashrrev_i32_e32 v5, 31, v4
	v_mfma_f32_16x16x32_bf16 v[24:27], v[150:153], v[48:51], v[24:27]
	v_cvt_pk_bf16_f32 v0, v16, v17
	v_cvt_pk_bf16_f32 v1, v18, v19
	v_cvt_pk_bf16_f32 v2, v20, v21
	v_cvt_pk_bf16_f32 v3, v22, v23
	s_nop 0
	v_permlane16_swap_b32_e32 v0, v2
	v_permlane16_swap_b32_e32 v1, v3
	v_lshl_add_u64 v[4:5], v[4:5], 1, s[44:45]
	global_store_dwordx4 v[4:5], v[0:3], off
	v_add_u32_e32 v4, v8, v58
	v_ashrrev_i32_e32 v5, 31, v4
	v_cvt_pk_bf16_f32 v0, v32, v33
	v_cvt_pk_bf16_f32 v1, v34, v35
	v_cvt_pk_bf16_f32 v2, v24, v25
	v_cvt_pk_bf16_f32 v3, v26, v27
	s_nop 0
	v_permlane16_swap_b32_e32 v0, v2
	v_permlane16_swap_b32_e32 v1, v3
	v_lshl_add_u64 v[4:5], v[4:5], 1, s[44:45]
	global_store_dwordx4 v[4:5], v[0:3], off
	s_and_saveexec_b64 s[44:45], s[18:19]
	s_cbranch_execz .LBB0_285
	v_mov_b32_e32 v0, 0
	s_mov_b32 s34, -2
	v_mov_b32_e32 v2, v99
	v_mov_b32_e32 v1, v0
